# attention: K prefetched two tiles ahead through the idle third ring slot, V pieces issued before K pieces, end-of-step wait vmcnt(3)
# baseline (speedup 1.0000x reference)
; __device__ __forceinline__ void attn_body(const bf16_t* __restrict__ Qb, const bf16_t* __restrict__ KVb, int hcol, bf16_t* __restrict__ Ob, float* __restrict__ rsqa, int seq, char* lds) {
;   int tid_ = threadIdx.x; asm volatile("" : "+v"(tid_));
;   const int tid = tid_, wid = __builtin_amdgcn_readfirstlane(tid >> 6), lane = tid & 63, r32 = lane & 31, hi = lane >> 5;
;   char* V_lds = lds; char* K_lds = lds + 2 * SHM_V;
;   float* ws = (float*)(lds + 2 * SHM_V + 3 * SHM_K) + wid * 64; float* li_l = ws; float* al_l = ws + 32;
;   float m_reg = -1e30f, l_reg = 0; f32x16 o[4] = {}; bf16x8 qr[8];
;   char* qlds = lds + 2 * SHM_V + 3 * SHM_K + NW * 64 * 4 + wid * 4096 + lane * 16;
;   int kb[4];
; #pragma unroll
;   for (int dl = 0; dl < 4; ++dl) kb[dl] = r32 * 384 + ((dl * 32 + hi * 16) ^ (((r32 >> 1) & 7) << 4));
;   const bf16_t* Qw = Qb + (long)(wid * QBLK + r32) * LDQ + hi * 8;
; #pragma unroll
;   for (int d0 = 0; d0 < 8; ++d0) qr[d0] = *reinterpret_cast<const bf16x8*>(Qw + d0 * 16);
; #pragma unroll
;   for (int d0 = 8; d0 < 12; ++d0) *reinterpret_cast<bf16x8*>(qlds + (d0 - 8) * 1024) = *reinterpret_cast<const bf16x8*>(Qw + d0 * 16);
;   DmaCtx dc; dc.wid = wid; dc.srd = __builtin_amdgcn_make_buffer_rsrc((void*)KVb, (short)0, 0x7fffffff, 0x00020000);
; #pragma unroll
;   for (int i = 0; i < 3; ++i) { const int b = (wid + 8 * i) * 1024 + lane * 16, row = b / 384, x = b % 384, blk = x >> 7, ch = ((x & 127) >> 4) ^ ((row >> 1) & 7), col = blk * 64 + ch * 8;
;     dc.koff[i] = (unsigned)(row * LDKV + (col < 128 ? hcol + col : 2048 + (col - 128))) * 2u; }
; #pragma unroll
;   for (int i = 0; i < 2; ++i) { const int b = (wid + 8 * i) * 1024 + lane * 16, st_ = b >> 9, kk = (st_ >> 2) * 8 + ((b & 511) >> 6), c = (st_ & 3) * 32 + ((b & 63) >> 1);
;     const int k = (kk & ~0xC) | ((kk & 4) << 1) | ((kk & 8) >> 1);
;     dc.voff[i] = (unsigned)(k * LDKV + hcol + 128 + c) * 2u; }
;   const __attribute__((address_space(3))) char* vb0 = (const __attribute__((address_space(3))) char*)V_lds + v_rd_base(lane);
;   constexpr size_t TILEB = (size_t)KVBLK * LDKV * 2;
;     ...
;   f32x16 pA0, pA1, pB0, pB1; float alA, alB; bf16x8 pa0, pa1, pa2, pa3; SMState st; const int NT = seq / KVBLK;
;   DMAK(0, 0); DMAV(0, 0); DMAK(1, 1);
;   asm volatile("s_waitcnt vmcnt(3)" ::: "memory"); BAR();
.LBB0_654:
	s_lshl_b32 s36, s0, 8
	s_add_i32 s8, s6, s36
	s_ashr_i32 s9, s8, 31
	s_mul_i32 s1, s8, 0xc00
	s_mul_hi_i32 s0, s8, 0xc00
	s_add_u32 s4, s3, s1
	s_addc_u32 s5, s21, s0
	s_ashr_i32 s7, s6, 31
	s_mul_i32 s1, s6, 0x1080
	v_mov_b32_e32 v72, v168
	s_mul_hi_i32 s0, s6, 0x1080
	s_add_u32 s28, s20, s1
	s_addc_u32 s10, s87, s0
	v_readfirstlane_b32 s1, v72
	s_ashr_i32 s11, s1, 6
	v_and_b32_e32 v187, 31, v72
	s_lshl_b32 s0, s11, 5
	v_bfe_u32 v186, v72, 5, 1
	v_or_b32_e32 v2, s0, v187
	v_mov_b64_e32 v[0:1], s[4:5]
	v_lshlrev_b32_e32 v166, 4, v186
	v_mad_i64_i32 v[0:1], s[4:5], v2, s42, v[0:1]
	v_lshl_add_u64 v[16:17], v[0:1], 0, v[166:167]
	global_load_dwordx4 v[0:3], v[16:17], off offset:256
	global_load_dwordx4 v[4:7], v[16:17], off offset:288
	global_load_dwordx4 v[8:11], v[16:17], off offset:320
	global_load_dwordx4 v[12:15], v[16:17], off offset:352
	global_load_dwordx4 v[156:159], v[16:17], off
	global_load_dwordx4 v[152:155], v[16:17], off offset:32
	global_load_dwordx4 v[148:151], v[16:17], off offset:64
	global_load_dwordx4 v[144:147], v[16:17], off offset:96
	global_load_dwordx4 v[140:143], v[16:17], off offset:128
	global_load_dwordx4 v[136:139], v[16:17], off offset:160
	global_load_dwordx4 v[132:135], v[16:17], off offset:192
	global_load_dwordx4 v[128:131], v[16:17], off offset:224
	v_and_b32_e32 v96, 63, v72
	v_lshlrev_b32_e32 v18, 3, v72
	v_lshlrev_b32_e32 v73, 4, v96
	s_lshl_b32 s69, s11, 10
	v_and_b32_e32 v57, 0x70, v18
	s_lshl_b32 s4, s11, 12
	v_or_b32_e32 v18, s69, v73
	s_add_i32 s4, s4, 0
	v_mul_hi_i32 v19, v18, s43
	v_add_u32_e32 v20, 0x2000, v18
	s_add_i32 s4, s4, 0x1a800
	v_add_u32_e32 v21, 0x4000, v18
	v_lshrrev_b32_e32 v22, 31, v19
	v_ashrrev_i32_e32 v19, 6, v19
	v_mul_hi_i32 v23, v20, s43
	v_add_u32_e32 v192, s4, v73
	v_mul_hi_i32 v24, v21, s43
	v_add_u32_e32 v16, v19, v22
	v_lshrrev_b32_e32 v17, 31, v23
	v_ashrrev_i32_e32 v19, 6, v23
	v_lshrrev_b32_e32 v22, 31, v24
	v_mul_i32_i24_e32 v23, 0x180, v16
	v_add_u32_e32 v17, v19, v17
	v_sub_u32_e32 v18, v18, v23
	v_mul_i32_i24_e32 v19, 0x180, v17
	v_lshrrev_b32_e32 v25, 1, v16
	v_lshrrev_b32_e32 v26, 4, v18
	v_sub_u32_e32 v19, v20, v19
	v_lshrrev_b32_e32 v23, 1, v17
	v_ashrrev_i32_e32 v18, 1, v18
	v_xor_b32_e32 v20, v26, v25
	v_lshrrev_b32_e32 v25, 4, v19
	v_and_b32_e32 v18, 0xffffffc0, v18
	v_ashrrev_i32_e32 v19, 1, v19
	v_lshlrev_b32_e32 v20, 3, v20
	v_xor_b32_e32 v23, v25, v23
	v_and_b32_e32 v19, 0xffffffc0, v19
	v_and_or_b32 v18, v20, 56, v18
	v_lshlrev_b32_e32 v20, 3, v23
	v_cmp_gt_i32_e32 vcc, s40, v18
	v_mad_i32_i24 v16, v16, s44, v18
	v_and_or_b32 v18, v20, 56, v19
	v_cndmask_b32_e32 v23, v161, v163, vcc
	v_cmp_gt_i32_e32 vcc, s40, v18
	s_and_b32 s4, s1, 64
	v_add_lshl_u32 v194, v16, v23, 1
	v_cndmask_b32_e32 v16, v161, v163, vcc
	s_and_b32 s29, s10, 0xffff
	s_add_i32 s70, s69, 0
	v_mad_i32_i24 v17, v17, s44, v18
	v_lshlrev_b32_e32 v74, 3, v96
	s_add_i32 m0, s70, 0x8000
	v_add_lshl_u32 v195, v17, v16, 1
	v_and_b32_e32 v75, 24, v74
	s_add_i32 s71, s70, 0x2000
	v_mul_u32_u24_e32 v56, 0x180, v187
	v_bitop3_b32 v193, v166, v56, v57 bitop3:0xde
	v_add_u32_e32 v68, 0, v193
	v_or_b32_e32 v48, 64, v166
	v_bitop3_b32 v200, v48, v56, v57 bitop3:0xde
	v_add_u32_e32 v70, 0, v200
	v_or_b32_e32 v58, 0x60, v166
	v_bitop3_b32 v201, v58, v56, v57 bitop3:0xde
	v_add_u32_e32 v71, 0, v201
	s_waitcnt vmcnt(11)
	ds_write_b128 v192, v[0:3]
	s_waitcnt vmcnt(10)
	ds_write_b128 v192, v[4:7] offset:1024
	s_waitcnt vmcnt(9)
	ds_write_b128 v192, v[8:11] offset:2048
	s_waitcnt vmcnt(8)
	ds_write_b128 v192, v[12:15] offset:3072
	v_ashrrev_i32_e32 v0, 6, v24
	v_add_u32_e32 v0, v0, v22
	v_mul_i32_i24_e32 v1, 0x180, v0
	v_sub_u32_e32 v1, v21, v1
	v_lshrrev_b32_e32 v2, 4, v1
	v_lshrrev_b32_e32 v3, 1, v0
	v_xor_b32_e32 v2, v2, v3
	v_ashrrev_i32_e32 v1, 1, v1
	v_and_b32_e32 v1, 0xffffffc0, v1
	v_lshlrev_b32_e32 v2, 3, v2
	v_and_or_b32 v1, v2, 56, v1
	v_cmp_gt_i32_e32 vcc, s40, v1
	v_mad_i32_i24 v0, v0, s44, v1
	v_bitop3_b32 v1, s4, v165, v96 bitop3:0xc8
	s_ashr_i32 s4, s69, 8
	v_cndmask_b32_e32 v2, v161, v163, vcc
	s_and_b32 s5, s4, 0x3fffff0
	s_lshr_b32 s4, s4, 1
	v_add_lshl_u32 v196, v0, v2, 1
	v_bfe_u32 v0, v72, 2, 2
	v_lshrrev_b32_e32 v2, 1, v72
	s_and_b32 s4, s4, 4
	v_and_or_b32 v0, v2, 8, v0
	s_or_b32 s4, s5, s4
	v_or_b32_e32 v2, s4, v0
	s_add_i32 s4, s69, 0x2000
	s_ashr_i32 s5, s4, 8
	s_and_b32 s10, s5, 0x3fffff0
	s_lshr_b32 s5, s5, 1
	s_and_b32 s5, s5, 4
	s_or_b32 s5, s10, s5
	buffer_load_dwordx4 v194, s[28:31], 0 offen lds
	s_add_i32 m0, s70, 0xa000
	v_or3_b32 v1, v1, s41, v75
	v_mul_lo_u32 v2, v2, s44
	v_or_b32_e32 v0, s5, v0
	buffer_load_dwordx4 v195, s[28:31], 0 offen lds
	s_add_i32 m0, s70, 0xc000
	v_add_lshl_u32 v197, v1, v2, 1
	v_mul_lo_u32 v0, v0, s44
	buffer_load_dwordx4 v196, s[28:31], 0 offen lds
	s_mov_b32 m0, s70
	v_add_lshl_u32 v198, v0, v1, 1
	buffer_load_dwordx4 v197, s[28:31], 0 offen lds
	s_mov_b32 m0, s71
	s_add_i32 s5, s69, s45
	buffer_load_dwordx4 v198, s[28:31], 0 offen lds
	s_add_i32 m0, s70, 0xe000
	v_or_b32_e32 v8, 32, v166
	buffer_load_dwordx4 v194, s[28:31], s66 offen lds
	s_add_i32 m0, s45, s4
	v_bitop3_b32 v199, v8, v56, v57 bitop3:0xde
	buffer_load_dwordx4 v195, s[28:31], s66 offen lds
	s_add_i32 m0, s5, 0x4000
	v_add_u32_e32 v69, 0, v199
	buffer_load_dwordx4 v196, s[28:31], s66 offen lds
	s_mov_b32 s98, 0x84000
	s_add_i32 m0, s70, 0x14000
	s_nop 0
	buffer_load_dwordx4 v194, s[28:31], s98 offen lds
	s_add_i32 m0, s70, 0x16000
	s_nop 0
	buffer_load_dwordx4 v195, s[28:31], s98 offen lds
	s_add_i32 m0, s70, 0x18000
	s_nop 0
	buffer_load_dwordx4 v196, s[28:31], s98 offen lds
	s_waitcnt vmcnt(6)
	s_waitcnt lgkmcnt(0)
	s_barrier
; #define DMAK(t, s) do { dc.gk = (unsigned)((size_t)(t) * TILEB); dc.kd = K_lds + (s) * SHM_K; dma_piece<0>(dc); dma_piece<1>(dc); dma_piece<2>(dc); } while (0)
; #define DMAV(t, s) do { dc.gv = (unsigned)((size_t)(t) * TILEB); dc.vd = V_lds + (s) * SHM_V; dma_piece<3>(dc); dma_piece<4>(dc); } while (0)
; #define BAR() do { asm volatile("s_waitcnt lgkmcnt(0)" ::: "memory"); __builtin_amdgcn_s_barrier(); asm volatile("" ::: "memory"); } while (0)
; __device__ __forceinline__ void qkt(f32x16& p0, f32x16& p1, const char* Ks, const bf16x8* qr, const char* qlds, const int* kb) {
;   p0 = f32x16{}; p1 = f32x16{};
; #pragma unroll
;   for (int d0 = 0; d0 < 12; ++d0) { const int off = kb[d0 & 3] + (d0 >> 2) * 128;
;     bf16x8 b0 = *reinterpret_cast<const bf16x8*>(Ks + off);
;     bf16x8 b1 = *reinterpret_cast<const bf16x8*>(Ks + off + 32 * 384);
;     bf16x8 q; if (d0 < 8) q = qr[d0]; else q = *reinterpret_cast<const bf16x8*>(qlds + (d0 - 8) * 1024);
;     p0 = __builtin_amdgcn_mfma_f32_32x32x16_bf16(b0, q, p0, 0, 0, 0);
;     p1 = __builtin_amdgcn_mfma_f32_32x32x16_bf16(b1, q, p1, 0, 0, 0); }
; }
; __device__ __forceinline__ void attn_body(const bf16_t* __restrict__ Qb, const bf16_t* __restrict__ KVb, int hcol, bf16_t* __restrict__ Ob, float* __restrict__ rsqa, int seq, char* lds) {
;     ...
;   DMAK(0, 0); DMAV(0, 0); DMAK(1, 1);
;   asm volatile("s_waitcnt vmcnt(3)" ::: "memory"); BAR();
;   qkt(pA0, pA1, K_lds, qr, qlds, kb); partialSM0(pA0, pA1, m_reg); alA = 1.f;
;   asm volatile("s_waitcnt vmcnt(0)" ::: "memory"); BAR();
	ds_read_b128 v[0:3], v68 offset:32768
	ds_read_b128 v[4:7], v68 offset:32896
	s_waitcnt vmcnt(15) lgkmcnt(1)
	v_mfma_f32_32x32x16_bf16 v[16:31], v[0:3], v[156:159], 0
	ds_read_b128 v[0:3], v68 offset:45056
	ds_read_b128 v[8:11], v68 offset:33024
	s_and_b32 s1, s1, 0x3fffffc0
	s_mov_b32 s49, s48
	s_lshl_b32 s1, s1, 2
	s_mov_b32 s50, s48
	s_mov_b32 s51, s48
	s_waitcnt lgkmcnt(1)
	v_mfma_f32_32x32x16_bf16 v[32:47], v[0:3], v[156:159], 0
	ds_read_b128 v[0:3], v69 offset:32768
	ds_read_b128 v[12:15], v69 offset:32896
	ds_read_b128 v[48:51], v69 offset:33024
	s_mov_b32 s52, s48
	s_mov_b32 s53, s48
	s_mov_b32 s54, s48
	s_mov_b32 s55, s48
	s_mov_b32 s56, s48
	s_waitcnt vmcnt(14) lgkmcnt(2)
	v_mfma_f32_32x32x16_bf16 v[16:31], v[0:3], v[152:155], v[16:31]
	ds_read_b128 v[0:3], v69 offset:45056
	s_mov_b32 s57, s48
	s_mov_b32 s58, s48
	s_mov_b32 s59, s48
	s_mov_b32 s60, s48
	s_mov_b32 s61, s48
	s_mov_b32 s62, s48
	s_waitcnt lgkmcnt(0)
	v_mfma_f32_32x32x16_bf16 v[32:47], v[0:3], v[152:155], v[32:47]
	ds_read_b128 v[0:3], v70 offset:32768
	ds_read_b128 v[52:55], v70 offset:32896
	ds_read_b128 v[56:59], v70 offset:33024
	s_mov_b32 s63, s48
	s_add_i32 s1, s1, 0
	s_add_i32 s1, s1, 0x1a000
	s_mov_b32 s72, 2
	s_mov_b32 s73, 1
	s_waitcnt vmcnt(13) lgkmcnt(2)
	v_mfma_f32_32x32x16_bf16 v[16:31], v[0:3], v[148:151], v[16:31]
	ds_read_b128 v[0:3], v70 offset:45056
	v_cmp_gt_u32_e64 s[4:5], 32, v96
	v_lshl_add_u32 v189, v187, 2, s1
	v_mov_b32_e32 v202, 1.0
	v_mov_b32_e32 v190, 0
	s_waitcnt lgkmcnt(0)
	v_mfma_f32_32x32x16_bf16 v[32:47], v[0:3], v[148:151], v[32:47]
	ds_read_b128 v[0:3], v71 offset:32768
	ds_read_b128 v[60:63], v71 offset:32896
	s_waitcnt vmcnt(12) lgkmcnt(1)
	v_mfma_f32_32x32x16_bf16 v[16:31], v[0:3], v[144:147], v[16:31]
	ds_read_b128 v[0:3], v71 offset:45056
	ds_read_b128 v[64:67], v71 offset:33024
	s_waitcnt lgkmcnt(1)
	v_mfma_f32_32x32x16_bf16 v[32:47], v[0:3], v[144:147], v[32:47]
	s_waitcnt vmcnt(11)
	v_mfma_f32_32x32x16_bf16 v[16:31], v[4:7], v[140:143], v[16:31]
	ds_read_b128 v[0:3], v68 offset:45184
	ds_read_b128 v[4:7], v68 offset:45312
	s_waitcnt lgkmcnt(1)
	v_mfma_f32_32x32x16_bf16 v[32:47], v[0:3], v[140:143], v[32:47]
	s_waitcnt vmcnt(10)
	v_mfma_f32_32x32x16_bf16 v[16:31], v[12:15], v[136:139], v[16:31]
	ds_read_b128 v[0:3], v69 offset:45184
	ds_read_b128 v[12:15], v69 offset:45312
	s_waitcnt lgkmcnt(1)
	v_mfma_f32_32x32x16_bf16 v[32:47], v[0:3], v[136:139], v[32:47]
	s_waitcnt vmcnt(9)
	v_mfma_f32_32x32x16_bf16 v[16:31], v[52:55], v[132:135], v[16:31]
	ds_read_b128 v[0:3], v70 offset:45184
	ds_read_b128 v[52:55], v70 offset:45312
	s_waitcnt lgkmcnt(1)
	v_mfma_f32_32x32x16_bf16 v[32:47], v[0:3], v[132:135], v[32:47]
	s_waitcnt vmcnt(8)
	v_mfma_f32_32x32x16_bf16 v[16:31], v[60:63], v[128:131], v[16:31]
	ds_read_b128 v[0:3], v71 offset:45184
	ds_read_b128 v[60:63], v71 offset:45312
	s_waitcnt lgkmcnt(1)
	v_mfma_f32_32x32x16_bf16 v[32:47], v[0:3], v[128:131], v[32:47]
	ds_read_b128 v[0:3], v192
	ds_read_b128 v[68:71], v192 offset:1024
	s_waitcnt lgkmcnt(1)
	v_mfma_f32_32x32x16_bf16 v[16:31], v[8:11], v[0:3], v[16:31]
	v_mfma_f32_32x32x16_bf16 v[32:47], v[4:7], v[0:3], v[32:47]
	ds_read_b128 v[0:3], v192 offset:2048
	v_lshlrev_b32_e32 v5, 1, v72
	v_and_b32_e32 v4, 0xc0, v73
	v_and_b32_e32 v6, 0x100, v74
	v_add3_u32 v4, 0, v75, v4
	v_and_b32_e32 v5, 32, v5
	v_add3_u32 v188, v4, v5, v6
	s_waitcnt lgkmcnt(1)
	v_mfma_f32_32x32x16_bf16 v[16:31], v[48:51], v[68:71], v[16:31]
	ds_read_b128 v[48:51], v192 offset:3072
	s_waitcnt vmcnt(3)
	s_waitcnt lgkmcnt(0)
	s_barrier
; #define BAR() do { asm volatile("s_waitcnt lgkmcnt(0)" ::: "memory"); __builtin_amdgcn_s_barrier(); asm volatile("" ::: "memory"); } while (0)
; __device__ __forceinline__ void partialSM0(f32x16& p0, f32x16& p1, float& M) {
;   float pmax = p0[0];
; #pragma unroll
;   for (int r = 1; r < 16; ++r) pmax = fmaxf(pmax, p0[r]);
; #pragma unroll
;   for (int r = 0; r < 16; ++r) pmax = fmaxf(pmax, p1[r]);
;   { auto rr = __builtin_amdgcn_permlane32_swap(__float_as_uint(pmax), __float_as_uint(pmax), false, false);
;     pmax = fmaxf(__uint_as_float(rr[0]), __uint_as_float(rr[1])); }
;   M = pmax;
; #pragma unroll
;   for (int r = 0; r < 16; ++r) { p0[r] -= pmax; p1[r] -= pmax; }
; #pragma unroll
;   for (int r = 0; r < 16; ++r) p0[r] = __builtin_amdgcn_exp2f(p0[r]);
; }
; __device__ __forceinline__ void attn_body(const bf16_t* __restrict__ Qb, const bf16_t* __restrict__ KVb, int hcol, bf16_t* __restrict__ Ob, float* __restrict__ rsqa, int seq, char* lds) {
;     ...
;   qkt(pA0, pA1, K_lds, qr, qlds, kb); partialSM0(pA0, pA1, m_reg); alA = 1.f;
;   asm volatile("s_waitcnt vmcnt(0)" ::: "memory"); BAR();
;   int sc = 1;
;   for (int j = 1; j + 1 < NT; j += 2) {
	v_mfma_f32_32x32x16_bf16 v[32:47], v[12:15], v[68:71], v[32:47]
	s_waitcnt lgkmcnt(1)
	v_mfma_f32_32x32x16_bf16 v[16:31], v[56:59], v[0:3], v[16:31]
	v_mfma_f32_32x32x16_bf16 v[32:47], v[52:55], v[0:3], v[32:47]
	v_mov_b64_e32 v[0:1], s[48:49]
	v_mov_b64_e32 v[14:15], s[62:63]
	v_mov_b64_e32 v[2:3], s[50:51]
	v_mov_b64_e32 v[4:5], s[52:53]
	v_mov_b64_e32 v[6:7], s[54:55]
	v_mov_b64_e32 v[8:9], s[56:57]
	v_mov_b64_e32 v[10:11], s[58:59]
	s_waitcnt lgkmcnt(0)
	v_mfma_f32_32x32x16_bf16 v[16:31], v[64:67], v[48:51], v[16:31]
	v_mov_b64_e32 v[12:13], s[60:61]
	s_add_i32 s50, s70, 0x4000
	s_add_i32 s49, s70, 0x6000
	s_mov_b32 s51, 0x84000
	v_mfma_f32_32x32x16_bf16 v[32:47], v[60:63], v[48:51], v[32:47]
	s_nop 6
	v_max_f32_e32 v48, v17, v17
	v_max_f32_e32 v49, v16, v16
	v_max_f32_e32 v48, v49, v48
	v_max3_f32 v48, v48, v18, v19
	v_max3_f32 v48, v48, v20, v21
	v_max3_f32 v48, v48, v22, v23
	v_max3_f32 v48, v48, v24, v25
	v_max3_f32 v48, v48, v26, v27
	v_max3_f32 v48, v48, v28, v29
	v_max3_f32 v48, v48, v30, v31
	v_max3_f32 v48, v48, v32, v33
	v_max3_f32 v48, v48, v34, v35
	v_max3_f32 v48, v48, v36, v37
	v_max3_f32 v48, v48, v38, v39
	v_max3_f32 v48, v48, v40, v41
	v_max3_f32 v48, v48, v42, v43
	v_max3_f32 v48, v48, v44, v45
	v_max3_f32 v48, v48, v46, v47
	v_mov_b32_e32 v49, v48
	s_nop 1
	v_permlane32_swap_b32_e32 v48, v49
	v_max_f32_e32 v49, v49, v49
	v_max_f32_e32 v48, v48, v48
	v_max_f32_e32 v191, v48, v49
	v_sub_f32_e32 v16, v16, v191
	v_exp_f32_e32 v64, v16
	v_sub_f32_e32 v16, v17, v191
	v_exp_f32_e32 v65, v16
	v_sub_f32_e32 v16, v18, v191
	v_exp_f32_e32 v66, v16
	v_sub_f32_e32 v16, v19, v191
	v_exp_f32_e32 v67, v16
	v_sub_f32_e32 v16, v20, v191
	v_exp_f32_e32 v68, v16
	v_sub_f32_e32 v16, v21, v191
	v_exp_f32_e32 v69, v16
	v_sub_f32_e32 v16, v22, v191
	v_exp_f32_e32 v70, v16
	v_sub_f32_e32 v16, v23, v191
	v_exp_f32_e32 v71, v16
	v_sub_f32_e32 v16, v24, v191
	v_exp_f32_e32 v72, v16
	v_sub_f32_e32 v16, v25, v191
	v_exp_f32_e32 v73, v16
	v_sub_f32_e32 v16, v26, v191
	v_exp_f32_e32 v74, v16
	v_sub_f32_e32 v16, v27, v191
	v_exp_f32_e32 v75, v16
	v_sub_f32_e32 v16, v28, v191
	v_exp_f32_e32 v76, v16
	v_sub_f32_e32 v16, v29, v191
	v_exp_f32_e32 v77, v16
	v_sub_f32_e32 v16, v30, v191
	v_exp_f32_e32 v78, v16
	v_sub_f32_e32 v16, v31, v191
	v_exp_f32_e32 v79, v16
	v_sub_f32_e32 v95, v47, v191
	v_sub_f32_e32 v94, v46, v191
	v_sub_f32_e32 v93, v45, v191
	v_sub_f32_e32 v92, v44, v191
	v_sub_f32_e32 v91, v43, v191
	v_sub_f32_e32 v90, v42, v191
	v_sub_f32_e32 v89, v41, v191
	v_sub_f32_e32 v88, v40, v191
	v_sub_f32_e32 v87, v39, v191
	v_sub_f32_e32 v86, v38, v191
	v_sub_f32_e32 v85, v37, v191
	v_sub_f32_e32 v84, v36, v191
	v_sub_f32_e32 v83, v35, v191
	v_sub_f32_e32 v82, v34, v191
	v_sub_f32_e32 v81, v33, v191
	v_sub_f32_e32 v80, v32, v191
	v_mov_b64_e32 v[62:63], v[14:15]
	v_mov_b64_e32 v[46:47], v[14:15]
	v_mov_b64_e32 v[30:31], v[14:15]
	v_mov_b64_e32 v[60:61], v[12:13]
	v_mov_b64_e32 v[58:59], v[10:11]
	v_mov_b64_e32 v[56:57], v[8:9]
	v_mov_b64_e32 v[54:55], v[6:7]
	v_mov_b64_e32 v[52:53], v[4:5]
	v_mov_b64_e32 v[50:51], v[2:3]
	v_mov_b64_e32 v[48:49], v[0:1]
	v_mov_b64_e32 v[44:45], v[12:13]
	v_mov_b64_e32 v[42:43], v[10:11]
	v_mov_b64_e32 v[40:41], v[8:9]
	v_mov_b64_e32 v[38:39], v[6:7]
	v_mov_b64_e32 v[36:37], v[4:5]
	v_mov_b64_e32 v[34:35], v[2:3]
	v_mov_b64_e32 v[32:33], v[0:1]
	v_mov_b64_e32 v[28:29], v[12:13]
	v_mov_b64_e32 v[26:27], v[10:11]
	v_mov_b64_e32 v[24:25], v[8:9]
	v_mov_b64_e32 v[22:23], v[6:7]
	v_mov_b64_e32 v[20:21], v[4:5]
	v_mov_b64_e32 v[18:19], v[2:3]
	v_mov_b64_e32 v[16:17], v[0:1]

; template <int I> __device__ __forceinline__ void fs_chunk(f32x16& p0, f32x16& p1, float alpha, float& l_reg, SMState& st, bf16x8& pa0, bf16x8& pa1, bf16x8& pa2, bf16x8& pa3) {
;     ...
;   if constexpr (I < 4) {
; #pragma unroll
;     for (int r = 4 * I; r < 4 * I + 4; ++r) p1[r] = __builtin_amdgcn_exp2f(p1[r]);
;     if constexpr (I == 0) st.ps = 0.f;
;   } else if constexpr (I < 8) { constexpr int j = 4 * (I - 4);
; #pragma unroll
;     for (int r = j; r < j + 4; ++r) st.ps += p0[r];
; #pragma unroll
;     for (int r = j; r < j + 4; ++r) st.ps += p1[r];
;   } else if constexpr (I == 8) {
;     const float ps_ = st.ps;
;     auto rr = __builtin_amdgcn_permlane32_swap(__float_as_uint(ps_), __float_as_uint(ps_), false, false);
;     l_reg = l_reg * alpha + (__uint_as_float(rr[0]) + __uint_as_float(rr[1]));
;     PK4(p0, 0, pa0);
; template <int D0> __device__ __forceinline__ void kq_load(bf16x8& b0, bf16x8& b1, bf16x8& q, const char* Ks, const bf16x8* qr, const char* qlds, const int* kb) {
;   const int off = kb[D0 & 3] + (D0 >> 2) * 128;
;   b0 = *reinterpret_cast<const bf16x8*>(Ks + off); b1 = *reinterpret_cast<const bf16x8*>(Ks + off + 32 * 384);
;   if constexpr (D0 < 8) q = qr[D0]; else q = *reinterpret_cast<const bf16x8*>(qlds + (D0 - 8) * 1024);
; }
; template <int P> __device__ __forceinline__ void dma_piece(const DmaCtx& c) {
;   if constexpr (P < 3) __builtin_amdgcn_raw_ptr_buffer_load_lds(c.srd, (lds_u32_t*)(c.kd + (c.wid + 8 * P) * 1024), 16, c.koff[P], c.gk, 0, 0);
;   else __builtin_amdgcn_raw_ptr_buffer_load_lds(c.srd, (lds_u32_t*)(c.vd + (c.wid + 8 * (P - 3)) * 1024), 16, c.voff[P - 3], c.gv, 0, 0);
; }
; template <int D0> __device__ __forceinline__ void h1_stage(f32x16& pc0, f32x16& pc1, f32x16& pp0, f32x16& pp1, float alP, float& l_reg, SMState& st, bf16x8& pa0, bf16x8& pa1, bf16x8& pa2, bf16x8& pa3, ...
;   bf16x8 m0, m1, mq;
;   if constexpr (D0 < 10) kq_load<D0 + 2>(m0, m1, mq, Ks, qr, qlds, kb);
;   pc0 = __builtin_amdgcn_mfma_f32_32x32x16_bf16(b0, q, pc0, 0, 0, 0);
;   pc1 = __builtin_amdgcn_mfma_f32_32x32x16_bf16(b1, q, pc1, 0, 0, 0);
;   if constexpr (D0 >= 1 && D0 <= 5) dma_piece<D0 - 1>(dc);
;   SBAR(); fs_chunk<D0>(pp0, pp1, alP, l_reg, st, pa0, pa1, pa2, pa3); SBAR();
;   if constexpr (D0 < 11) h1_stage<D0 + 1>(pc0, pc1, pp0, pp1, alP, l_reg, st, pa0, pa1, pa2, pa3, n0, n1, nq, m0, m1, mq, Ks, qr, qlds, kb, dc);
; }
.Lattn_m2:
	v_xor_b32_e32 v112, 0x80000000, v191
	v_mov_b32_e32 v113, v112
	v_mov_b32_e32 v114, v112
	v_mov_b32_e32 v115, v112
	v_mov_b32_e32 v116, v112
	v_mov_b32_e32 v117, v112
	v_mov_b32_e32 v118, v112
	v_mov_b32_e32 v119, v112
	v_mov_b32_e32 v120, v112
	v_mov_b32_e32 v121, v112
	v_mov_b32_e32 v122, v112
	v_mov_b32_e32 v123, v112
	v_mov_b32_e32 v124, v112
	v_mov_b32_e32 v125, v112
	v_mov_b32_e32 v126, v112
	v_mov_b32_e32 v127, v112
	v_add_u32_e32 v224, s10, v199
	v_add_u32_e32 v225, s10, v200
	s_waitcnt lgkmcnt(1)
	v_mfma_f32_32x32x16_bf16 v[96:111], v[204:207], v[156:159], v[112:127]
	ds_read_b128 v[204:207], v224 offset:32768
	ds_read_b128 v[212:215], v224 offset:45056
	ds_read_b128 v[216:219], v225 offset:32768
	ds_read_b128 v[220:223], v225 offset:45056
	s_mul_i32 s11, s52, 0x6000
	s_add_i32 s53, s11, 0
	s_add_i32 s11, s51, 0xfffbe000
	s_waitcnt lgkmcnt(4)
	v_mfma_f32_32x32x16_bf16 v[112:127], v[208:211], v[156:159], v[112:127]
	v_exp_f32_e32 v226, v80
	v_exp_f32_e32 v227, v81
	v_exp_f32_e32 v228, v82
	v_exp_f32_e32 v229, v83
	v_add_u32_e32 v230, s10, v201
	s_add_i32 s98, s52, 1
	s_cmp_lg_u32 s52, 2
	s_cselect_b32 s98, s98, 0
	s_mul_i32 s98, s98, 0x6000
	s_add_i32 s10, s98, s69
	s_add_i32 s98, s51, 0x42000
	s_mov_b32 m0, s50
	ds_read_b128 v[80:83], v230 offset:32768
	ds_read_b128 v[208:211], v230 offset:45056
	buffer_load_dwordx4 v197, s[28:31], s11 offen lds
	s_waitcnt lgkmcnt(5)
	v_mfma_f32_32x32x16_bf16 v[96:111], v[204:207], v[152:155], v[96:111]
	s_waitcnt lgkmcnt(4)
	v_mfma_f32_32x32x16_bf16 v[112:127], v[212:215], v[152:155], v[112:127]
	v_exp_f32_e32 v231, v84
	v_exp_f32_e32 v232, v85
	v_exp_f32_e32 v233, v86
	v_exp_f32_e32 v234, v87
	s_mov_b32 m0, s49
	ds_read_b128 v[84:87], v203 offset:32896
	ds_read_b128 v[204:207], v203 offset:45184
	buffer_load_dwordx4 v198, s[28:31], s11 offen lds
	s_waitcnt lgkmcnt(5)
	v_mfma_f32_32x32x16_bf16 v[96:111], v[216:219], v[148:151], v[96:111]
	s_waitcnt lgkmcnt(4)
	v_mfma_f32_32x32x16_bf16 v[112:127], v[220:223], v[148:151], v[112:127]
	v_exp_f32_e32 v235, v88
	v_exp_f32_e32 v236, v89
	v_exp_f32_e32 v237, v90
	v_exp_f32_e32 v238, v91
	s_add_i32 m0, s10, 0x8000
	ds_read_b128 v[88:91], v224 offset:32896
	ds_read_b128 v[212:215], v224 offset:45184
	buffer_load_dwordx4 v194, s[28:31], s98 offen lds
	s_waitcnt lgkmcnt(5)
	v_mfma_f32_32x32x16_bf16 v[96:111], v[80:83], v[144:147], v[96:111]
	s_waitcnt lgkmcnt(4)
	v_mfma_f32_32x32x16_bf16 v[112:127], v[208:211], v[144:147], v[112:127]
	v_exp_f32_e32 v239, v92
	v_exp_f32_e32 v240, v93
	v_exp_f32_e32 v241, v94
	v_exp_f32_e32 v242, v95
	s_add_i32 m0, s10, 0xa000
	ds_read_b128 v[80:83], v225 offset:32896
	ds_read_b128 v[92:95], v225 offset:45184
	buffer_load_dwordx4 v195, s[28:31], s98 offen lds
	s_waitcnt lgkmcnt(5)
	v_mfma_f32_32x32x16_bf16 v[96:111], v[84:87], v[140:143], v[96:111]
	s_waitcnt lgkmcnt(4)
	v_mfma_f32_32x32x16_bf16 v[112:127], v[204:207], v[140:143], v[112:127]
	v_add_f32_e32 v84, 0, v64
	v_add_f32_e32 v84, v65, v84
	v_add_f32_e32 v84, v66, v84
	v_add_f32_e32 v84, v67, v84
	v_add_f32_e32 v84, v226, v84
	v_add_f32_e32 v84, v227, v84
	v_add_f32_e32 v84, v228, v84
	v_add_f32_e32 v208, v229, v84
	s_add_i32 m0, s10, 0xc000
	ds_read_b128 v[84:87], v230 offset:32896
	ds_read_b128 v[204:207], v230 offset:45184
	buffer_load_dwordx4 v196, s[28:31], s98 offen lds
	s_waitcnt lgkmcnt(5)
	v_mfma_f32_32x32x16_bf16 v[96:111], v[88:91], v[136:139], v[96:111]
	s_waitcnt lgkmcnt(4)
	v_mfma_f32_32x32x16_bf16 v[112:127], v[212:215], v[136:139], v[112:127]
	v_add_f32_e32 v88, v68, v208
	v_add_f32_e32 v88, v69, v88
	v_add_f32_e32 v88, v70, v88
	v_add_f32_e32 v88, v71, v88
	v_add_f32_e32 v88, v231, v88
	v_add_f32_e32 v88, v232, v88
	v_add_f32_e32 v88, v233, v88
	v_add_f32_e32 v212, v234, v88
	s_waitcnt lgkmcnt(3)
	v_mfma_f32_32x32x16_bf16 v[96:111], v[80:83], v[132:135], v[96:111]
	ds_read_b128 v[80:83], v203 offset:45312
	ds_read_b128 v[88:91], v203 offset:33024
	ds_read_b128 v[208:211], v192
	s_waitcnt lgkmcnt(5)
	v_mfma_f32_32x32x16_bf16 v[112:127], v[92:95], v[132:135], v[112:127]
	v_add_f32_e32 v92, v72, v212
	v_add_f32_e32 v92, v73, v92
	v_add_f32_e32 v92, v74, v92
	v_add_f32_e32 v92, v75, v92
	v_add_f32_e32 v92, v235, v92
	v_add_f32_e32 v92, v236, v92
	v_add_f32_e32 v92, v237, v92
	v_add_f32_e32 v203, v238, v92
	s_waitcnt lgkmcnt(4)
	v_mfma_f32_32x32x16_bf16 v[96:111], v[84:87], v[128:131], v[96:111]
	ds_read_b128 v[84:87], v224 offset:45312
	ds_read_b128 v[92:95], v224 offset:33024
	ds_read_b128 v[212:215], v192 offset:1024
	s_waitcnt lgkmcnt(6)
	v_mfma_f32_32x32x16_bf16 v[112:127], v[204:207], v[128:131], v[112:127]
	v_add_f32_e32 v203, v76, v203
	v_add_f32_e32 v203, v77, v203
	v_add_f32_e32 v203, v78, v203
	v_add_f32_e32 v203, v79, v203
	v_add_f32_e32 v203, v239, v203
	v_add_f32_e32 v203, v240, v203
	v_add_f32_e32 v203, v241, v203
	v_add_f32_e32 v203, v242, v203
	s_waitcnt lgkmcnt(3)
	v_mfma_f32_32x32x16_bf16 v[96:111], v[88:91], v[208:211], v[96:111]
	ds_read_b128 v[88:91], v225 offset:45312
	ds_read_b128 v[216:219], v225 offset:33024
	ds_read_b128 v[220:223], v192 offset:2048
	v_mfma_f32_32x32x16_bf16 v[112:127], v[80:83], v[208:211], v[112:127]
	v_mov_b32_e32 v204, v203
	v_cvt_pk_bf16_f32 v80, v64, v65
	v_cvt_pk_bf16_f32 v81, v66, v67
	v_cvt_pk_bf16_f32 v82, v68, v69
	v_cvt_pk_bf16_f32 v83, v70, v71
	v_permlane32_swap_b32_e32 v203, v204
	v_permlane32_swap_b32_e32 v80, v82
	v_permlane32_swap_b32_e32 v81, v83
	s_waitcnt lgkmcnt(3)
; #define SBAR() __builtin_amdgcn_sched_barrier(0)
; template <int I> __device__ __forceinline__ void ps_chunk(f32x16& p0, f32x16& p1, float& M, float& alpha, SMState& st) {
;   if constexpr (I == 0) { float m = p0[0];
; #pragma unroll
;     for (int r = 1; r < 16; ++r) m = fmaxf(m, p0[r]);
;     st.pmax = m;
;   } else if constexpr (I == 1) { float m = st.pmax;
; #pragma unroll
;     for (int r = 0; r < 16; ++r) m = fmaxf(m, p1[r]);
;     auto rr = __builtin_amdgcn_permlane32_swap(__float_as_uint(m), __float_as_uint(m), false, false);
;     st.pmax = fmaxf(__uint_as_float(rr[0]), __uint_as_float(rr[1]));
;   } else if constexpr (I == 2) {
;     alpha = 1.f;
;     if (__builtin_expect(!__all(st.pmax <= THR2), 0)) { const float d = fmaxf(st.pmax, 0.f); M += d; alpha = __builtin_amdgcn_exp2f(-d);
; #pragma unroll
;       for (int r = 0; r < 16; ++r) { p0[r] -= d; p1[r] -= d; } }
; template <int G> __device__ __forceinline__ void v_load(s16x4& la, s16x4& ha, s16x4& lb, s16x4& hb, const __attribute__((address_space(3))) char* vb) {
;   constexpr int ks = G >> 1, d0 = (G & 1) * 2;
;   la = __builtin_amdgcn_ds_read_tr16_b64_v4i16((lds_s16x4b*)(vb + v_rd_off(d0, ks, 0))); ha = __builtin_amdgcn_ds_read_tr16_b64_v4i16((lds_s16x4b*)(vb + v_rd_off(d0, ks, 1)));
;   lb = __builtin_amdgcn_ds_read_tr16_b64_v4i16((lds_s16x4b*)(vb + v_rd_off(d0 + 1, ks, 0))); hb = __builtin_amdgcn_ds_read_tr16_b64_v4i16((lds_s16x4b*)(vb + v_rd_off(d0 + 1, ks, 1)));
; }
; template <int G> __device__ __forceinline__ void h2_stage(f32x16* o, f32x16& pc0, f32x16& pc1, float& m_reg, float& alC, SMState& st, bf16x8 pa0, bf16x8 pa1, bf16x8 pa2, bf16x8 pa3, ...
;   constexpr int ks = G >> 1, d0 = (G & 1) * 2;
;   s16x4 nla, nha, nlb, nhb;
;   if constexpr (G < 7) v_load<G + 1>(nla, nha, nlb, nhb, vb);
;   const bf16x8 pa = ks == 0 ? pa0 : ks == 1 ? pa1 : ks == 2 ? pa2 : pa3;
;     ...
;   o[d0] = __builtin_amdgcn_mfma_f32_32x32x16_bf16(pa, PK(la, ha), o[d0], 0, 0, 0);
;   o[d0 + 1] = __builtin_amdgcn_mfma_f32_32x32x16_bf16(pa, PK(lb, hb), o[d0 + 1], 0, 0, 0);
;     ...
;   SBAR(); ps_chunk<G>(pc0, pc1, m_reg, alC, st); SBAR();
;   if constexpr (G < 7) h2_stage<G + 1>(o, pc0, pc1, m_reg, alC, st, pa0, pa1, pa2, pa3, nla, nha, nlb, nhb, vb);
; }
	v_mfma_f32_32x32x16_bf16 v[96:111], v[92:95], v[212:215], v[96:111]
	ds_read_b128 v[64:67], v192 offset:3072
	ds_read_b128 v[92:95], v230 offset:33024
	ds_read_b128 v[206:209], v230 offset:45312
	v_mfma_f32_32x32x16_bf16 v[112:127], v[84:87], v[212:215], v[112:127]
	v_cvt_pk_bf16_f32 v72, v72, v73
	v_cvt_pk_bf16_f32 v73, v74, v75
	v_cvt_pk_bf16_f32 v74, v76, v77
	v_cvt_pk_bf16_f32 v75, v78, v79
	s_nop 0
	v_permlane32_swap_b32_e32 v72, v74
	v_permlane32_swap_b32_e32 v73, v75
	s_waitcnt lgkmcnt(3)
	v_mfma_f32_32x32x16_bf16 v[96:111], v[216:219], v[220:223], v[96:111]
	v_mfma_f32_32x32x16_bf16 v[112:127], v[88:91], v[220:223], v[112:127]
	v_cvt_pk_bf16_f32 v68, v226, v227
	v_cvt_pk_bf16_f32 v69, v228, v229
	v_cvt_pk_bf16_f32 v70, v231, v232
	v_cvt_pk_bf16_f32 v71, v233, v234
	s_nop 0
	v_permlane32_swap_b32_e32 v68, v70
	v_permlane32_swap_b32_e32 v69, v71
	s_waitcnt lgkmcnt(1)
	v_mfma_f32_32x32x16_bf16 v[96:111], v[92:95], v[64:67], v[96:111]
	s_waitcnt lgkmcnt(0)
	v_mfma_f32_32x32x16_bf16 v[112:127], v[206:209], v[64:67], v[112:127]
	v_cvt_pk_bf16_f32 v64, v235, v236
	v_cvt_pk_bf16_f32 v65, v237, v238
	v_cvt_pk_bf16_f32 v66, v239, v240
	v_cvt_pk_bf16_f32 v67, v241, v242
	s_nop 0
	v_permlane32_swap_b32_e32 v64, v66
	v_permlane32_swap_b32_e32 v65, v67
	ds_read_b64_tr_b16 v[78:79], v188 offset:2048
	ds_read_b64_tr_b16 v[76:77], v188
	ds_read_b64_tr_b16 v[84:85], v188 offset:512
	ds_read_b64_tr_b16 v[88:89], v188 offset:1024
	ds_read_b64_tr_b16 v[92:93], v188 offset:1536
	ds_read_b64_tr_b16 v[86:87], v188 offset:2560
	ds_read_b64_tr_b16 v[90:91], v188 offset:3072
	ds_read_b64_tr_b16 v[94:95], v188 offset:3584
	s_waitcnt lgkmcnt(6)
	v_mfma_f32_32x32x16_bf16 v[0:15], v[80:83], v[76:79], v[0:15]
	s_waitcnt lgkmcnt(2)
	v_mfma_f32_32x32x16_bf16 v[48:63], v[80:83], v[84:87], v[48:63]
	v_max_f32_e32 v76, v97, v97
	v_max_f32_e32 v77, v96, v96
	v_max_f32_e32 v76, v77, v76
	v_max3_f32 v76, v76, v98, v99
	v_max3_f32 v76, v76, v100, v101
	v_max3_f32 v76, v76, v102, v103
	v_max3_f32 v76, v76, v104, v105
	v_max3_f32 v76, v76, v106, v107
	v_max3_f32 v76, v76, v108, v109
	v_max3_f32 v84, v76, v110, v111
	s_waitcnt lgkmcnt(1)
	v_mfma_f32_32x32x16_bf16 v[32:47], v[80:83], v[88:91], v[32:47]
	ds_read_b64_tr_b16 v[76:77], v188 offset:4096
	ds_read_b64_tr_b16 v[78:79], v188 offset:6144
	ds_read_b64_tr_b16 v[88:89], v188 offset:6656
	ds_read_b64_tr_b16 v[86:87], v188 offset:4608
	s_waitcnt lgkmcnt(4)
	v_mfma_f32_32x32x16_bf16 v[16:31], v[80:83], v[92:95], v[16:31]
	v_max3_f32 v80, v84, v112, v113
	v_max3_f32 v80, v80, v114, v115
	v_max3_f32 v80, v80, v116, v117
	v_max3_f32 v80, v80, v118, v119
	v_max3_f32 v80, v80, v120, v121
	v_max3_f32 v80, v80, v122, v123
	v_max3_f32 v80, v80, v124, v125
	v_max3_f32 v80, v80, v126, v127
	v_mov_b32_e32 v81, v80
	s_nop 1
	v_permlane32_swap_b32_e32 v80, v81
	v_max_f32_e32 v81, v81, v81
	v_max_f32_e32 v80, v80, v80
	v_max_f32_e32 v84, v80, v81
	s_waitcnt lgkmcnt(2)
	v_mfma_f32_32x32x16_bf16 v[0:15], v[72:75], v[76:79], v[0:15]
	ds_read_b64_tr_b16 v[80:81], v188 offset:5120
	ds_read_b64_tr_b16 v[82:83], v188 offset:7168
	ds_read_b64_tr_b16 v[78:79], v188 offset:7680
	ds_read_b64_tr_b16 v[76:77], v188 offset:5632
	s_waitcnt lgkmcnt(4)
	v_mfma_f32_32x32x16_bf16 v[48:63], v[72:75], v[86:89], v[48:63]
	v_cmp_ge_f32_e32 vcc, s67, v84
	s_cmp_eq_u64 vcc, exec
	s_cbranch_scc0 .LBB0_668
	v_mov_b32_e32 v206, 1.0
; #define SBAR() __builtin_amdgcn_sched_barrier(0)
; template <int G> __device__ __forceinline__ void h2_stage(f32x16* o, f32x16& pc0, f32x16& pc1, float& m_reg, float& alC, SMState& st, bf16x8 pa0, bf16x8 pa1, bf16x8 pa2, bf16x8 pa3, ...
;   constexpr int ks = G >> 1, d0 = (G & 1) * 2;
;   s16x4 nla, nha, nlb, nhb;
;   if constexpr (G < 7) v_load<G + 1>(nla, nha, nlb, nhb, vb);
;   const bf16x8 pa = ks == 0 ? pa0 : ks == 1 ? pa1 : ks == 2 ? pa2 : pa3;
;     ...
;   o[d0] = __builtin_amdgcn_mfma_f32_32x32x16_bf16(pa, PK(la, ha), o[d0], 0, 0, 0);
;   o[d0 + 1] = __builtin_amdgcn_mfma_f32_32x32x16_bf16(pa, PK(lb, hb), o[d0 + 1], 0, 0, 0);
;     ...
;   SBAR(); ps_chunk<G>(pc0, pc1, m_reg, alC, st); SBAR();
;   if constexpr (G < 7) h2_stage<G + 1>(o, pc0, pc1, m_reg, alC, st, pa0, pa1, pa2, pa3, nla, nha, nlb, nhb, vb);
; }
.LBB0_657:
	v_exp_f32_e32 v96, v96
	v_exp_f32_e32 v97, v97
	s_waitcnt lgkmcnt(2)
	v_mfma_f32_32x32x16_bf16 v[32:47], v[72:75], v[80:83], v[32:47]
	ds_read_b64_tr_b16 v[80:81], v188 offset:8192
	ds_read_b64_tr_b16 v[82:83], v188 offset:10240
	ds_read_b64_tr_b16 v[86:87], v188 offset:10752
	ds_read_b64_tr_b16 v[84:85], v188 offset:8704
	s_waitcnt lgkmcnt(4)
	v_mfma_f32_32x32x16_bf16 v[16:31], v[72:75], v[76:79], v[16:31]
	v_exp_f32_e32 v98, v98
	v_exp_f32_e32 v99, v99
	v_exp_f32_e32 v100, v100
	s_waitcnt lgkmcnt(2)
	v_mfma_f32_32x32x16_bf16 v[0:15], v[68:71], v[80:83], v[0:15]
	ds_read_b64_tr_b16 v[72:73], v188 offset:9216
	ds_read_b64_tr_b16 v[74:75], v188 offset:11264
	ds_read_b64_tr_b16 v[78:79], v188 offset:11776
	ds_read_b64_tr_b16 v[76:77], v188 offset:9728
	s_waitcnt lgkmcnt(4)
	v_mfma_f32_32x32x16_bf16 v[48:63], v[68:71], v[84:87], v[48:63]
	v_exp_f32_e32 v101, v101
	v_exp_f32_e32 v102, v102
	v_exp_f32_e32 v103, v103
	s_waitcnt lgkmcnt(2)
	v_mfma_f32_32x32x16_bf16 v[32:47], v[68:71], v[72:75], v[32:47]
	ds_read_b64_tr_b16 v[72:73], v188 offset:12288
	ds_read_b64_tr_b16 v[74:75], v188 offset:14336
	ds_read_b64_tr_b16 v[82:83], v188 offset:14848
	ds_read_b64_tr_b16 v[80:81], v188 offset:12800
	s_waitcnt lgkmcnt(4)
	v_mfma_f32_32x32x16_bf16 v[16:31], v[68:71], v[76:79], v[16:31]
	v_exp_f32_e32 v104, v104
	v_exp_f32_e32 v105, v105
	v_exp_f32_e32 v106, v106
	s_waitcnt lgkmcnt(2)
	v_mfma_f32_32x32x16_bf16 v[0:15], v[64:67], v[72:75], v[0:15]
	ds_read_b64_tr_b16 v[68:69], v188 offset:13312
	ds_read_b64_tr_b16 v[70:71], v188 offset:15360
	ds_read_b64_tr_b16 v[74:75], v188 offset:15872
	ds_read_b64_tr_b16 v[72:73], v188 offset:13824
	s_waitcnt lgkmcnt(4)
	v_exp_f32_e32 v107, v107
	v_exp_f32_e32 v108, v108
	v_exp_f32_e32 v109, v109
	s_waitcnt lgkmcnt(0)
	v_exp_f32_e32 v110, v110
	v_exp_f32_e32 v111, v111
	s_waitcnt vmcnt(3)
	v_cmp_gt_f32_e32 vcc, 1.0, v206
	s_cbranch_vccz .Lattn_n1
	v_mfma_f32_32x32x16_bf16 v[48:63], v[64:67], v[80:83], v[48:63]
	v_mfma_f32_32x32x16_bf16 v[32:47], v[64:67], v[68:71], v[32:47]
	v_mfma_f32_32x32x16_bf16 v[16:31], v[64:67], v[72:75], v[16:31]
	s_nop 15
	s_nop 15
	s_and_saveexec_b64 s[10:11], s[4:5]
	ds_write_b32 v189, v206 offset:128
	s_or_b64 exec, exec, s[10:11]
	s_waitcnt lgkmcnt(0)
	v_add_u32_e32 v76, s1, v166
	ds_read_b128 v[64:67], v76 offset:224
	ds_read_b128 v[68:71], v76 offset:192
	ds_read_b128 v[72:75], v76 offset:160
	ds_read_b128 v[76:79], v76 offset:128
	s_waitcnt lgkmcnt(3)
	v_pk_mul_f32 v[12:13], v[12:13], v[64:65]
	s_waitcnt lgkmcnt(2)
	v_pk_mul_f32 v[8:9], v[8:9], v[68:69]
	s_waitcnt lgkmcnt(1)
	v_pk_mul_f32 v[4:5], v[4:5], v[72:73]
	v_pk_mul_f32 v[14:15], v[14:15], v[66:67]
	v_pk_mul_f32 v[10:11], v[10:11], v[70:71]
	v_pk_mul_f32 v[6:7], v[6:7], v[74:75]
	s_waitcnt lgkmcnt(0)
	v_pk_mul_f32 v[2:3], v[2:3], v[78:79]
	v_pk_mul_f32 v[0:1], v[0:1], v[76:77]
	v_pk_mul_f32 v[60:61], v[60:61], v[64:65]
	v_pk_mul_f32 v[56:57], v[56:57], v[68:69]
	v_pk_mul_f32 v[52:53], v[52:53], v[72:73]
	v_pk_mul_f32 v[62:63], v[62:63], v[66:67]
	v_pk_mul_f32 v[58:59], v[58:59], v[70:71]
	v_pk_mul_f32 v[54:55], v[54:55], v[74:75]
	v_pk_mul_f32 v[50:51], v[50:51], v[78:79]
	v_pk_mul_f32 v[48:49], v[48:49], v[76:77]
	v_pk_mul_f32 v[44:45], v[44:45], v[64:65]
	v_pk_mul_f32 v[40:41], v[40:41], v[68:69]
	v_pk_mul_f32 v[36:37], v[36:37], v[72:73]
	v_pk_mul_f32 v[46:47], v[46:47], v[66:67]
	v_pk_mul_f32 v[42:43], v[42:43], v[70:71]
	v_pk_mul_f32 v[38:39], v[38:39], v[74:75]
	v_pk_mul_f32 v[34:35], v[34:35], v[78:79]
	v_pk_mul_f32 v[32:33], v[32:33], v[76:77]
	v_pk_mul_f32 v[28:29], v[28:29], v[64:65]
	v_pk_mul_f32 v[24:25], v[24:25], v[68:69]
	v_pk_mul_f32 v[20:21], v[20:21], v[72:73]
	v_pk_mul_f32 v[30:31], v[30:31], v[66:67]
	v_pk_mul_f32 v[26:27], v[26:27], v[70:71]
	v_pk_mul_f32 v[22:23], v[22:23], v[74:75]
	v_pk_mul_f32 v[18:19], v[18:19], v[78:79]
	v_pk_mul_f32 v[16:17], v[16:17], v[76:77]
	s_waitcnt lgkmcnt(0)
	s_barrier
	v_add_u32_e32 v205, s53, v193
	ds_read_b128 v[208:211], v205 offset:32768
	ds_read_b128 v[212:215], v205 offset:45056
	s_branch .Lattn_m1

; template <int I> __device__ __forceinline__ void fs_chunk(f32x16& p0, f32x16& p1, float alpha, float& l_reg, SMState& st, bf16x8& pa0, bf16x8& pa1, bf16x8& pa2, bf16x8& pa3) {
;     ...
;   if constexpr (I < 4) {
; #pragma unroll
;     for (int r = 4 * I; r < 4 * I + 4; ++r) p1[r] = __builtin_amdgcn_exp2f(p1[r]);
;     if constexpr (I == 0) st.ps = 0.f;
;   } else if constexpr (I < 8) { constexpr int j = 4 * (I - 4);
; #pragma unroll
;     for (int r = j; r < j + 4; ++r) st.ps += p0[r];
; #pragma unroll
;     for (int r = j; r < j + 4; ++r) st.ps += p1[r];
;   } else if constexpr (I == 8) {
;     const float ps_ = st.ps;
;     auto rr = __builtin_amdgcn_permlane32_swap(__float_as_uint(ps_), __float_as_uint(ps_), false, false);
;     l_reg = l_reg * alpha + (__uint_as_float(rr[0]) + __uint_as_float(rr[1]));
;     PK4(p0, 0, pa0);
; template <int D0> __device__ __forceinline__ void kq_load(bf16x8& b0, bf16x8& b1, bf16x8& q, const char* Ks, const bf16x8* qr, const char* qlds, const int* kb) {
;   const int off = kb[D0 & 3] + (D0 >> 2) * 128;
;   b0 = *reinterpret_cast<const bf16x8*>(Ks + off); b1 = *reinterpret_cast<const bf16x8*>(Ks + off + 32 * 384);
;   if constexpr (D0 < 8) q = qr[D0]; else q = *reinterpret_cast<const bf16x8*>(qlds + (D0 - 8) * 1024);
; }
; template <int P> __device__ __forceinline__ void dma_piece(const DmaCtx& c) {
;   if constexpr (P < 3) __builtin_amdgcn_raw_ptr_buffer_load_lds(c.srd, (lds_u32_t*)(c.kd + (c.wid + 8 * P) * 1024), 16, c.koff[P], c.gk, 0, 0);
;   else __builtin_amdgcn_raw_ptr_buffer_load_lds(c.srd, (lds_u32_t*)(c.vd + (c.wid + 8 * (P - 3)) * 1024), 16, c.voff[P - 3], c.gv, 0, 0);
; }
; template <int D0> __device__ __forceinline__ void h1_stage(f32x16& pc0, f32x16& pc1, f32x16& pp0, f32x16& pp1, float alP, float& l_reg, SMState& st, bf16x8& pa0, bf16x8& pa1, bf16x8& pa2, bf16x8& pa3, ...
;   bf16x8 m0, m1, mq;
;   if constexpr (D0 < 10) kq_load<D0 + 2>(m0, m1, mq, Ks, qr, qlds, kb);
;   pc0 = __builtin_amdgcn_mfma_f32_32x32x16_bf16(b0, q, pc0, 0, 0, 0);
;   pc1 = __builtin_amdgcn_mfma_f32_32x32x16_bf16(b1, q, pc1, 0, 0, 0);
;   if constexpr (D0 >= 1 && D0 <= 5) dma_piece<D0 - 1>(dc);
;   SBAR(); fs_chunk<D0>(pp0, pp1, alP, l_reg, st, pa0, pa1, pa2, pa3); SBAR();
;   if constexpr (D0 < 11) h1_stage<D0 + 1>(pc0, pc1, pp0, pp1, alP, l_reg, st, pa0, pa1, pa2, pa3, n0, n1, nq, m0, m1, mq, Ks, qr, qlds, kb, dc);
; }
.Lattn_m1:
	v_xor_b32_e32 v80, 0x80000000, v191
	v_mov_b32_e32 v81, v80
	v_mov_b32_e32 v82, v80
	v_mov_b32_e32 v83, v80
	v_mov_b32_e32 v84, v80
	v_mov_b32_e32 v85, v80
	v_mov_b32_e32 v86, v80
	v_mov_b32_e32 v87, v80
	v_mov_b32_e32 v88, v80
	v_mov_b32_e32 v89, v80
	v_mov_b32_e32 v90, v80
	v_mov_b32_e32 v91, v80
	v_mov_b32_e32 v92, v80
	v_mov_b32_e32 v93, v80
	v_mov_b32_e32 v94, v80
	v_mov_b32_e32 v95, v80
	v_add_u32_e32 v207, s53, v199
	v_add_u32_e32 v228, s53, v200
	s_waitcnt lgkmcnt(1)
	v_mfma_f32_32x32x16_bf16 v[64:79], v[208:211], v[156:159], v[80:95]
	s_add_i32 s10, s51, 0x84000
	s_add_i32 s11, s52, 1
	ds_read_b128 v[208:211], v207 offset:32768
	ds_read_b128 v[216:219], v207 offset:45056
	ds_read_b128 v[220:223], v228 offset:32768
	ds_read_b128 v[224:227], v228 offset:45056
	s_cmp_lg_u32 s52, 2
	s_cselect_b32 s73, s11, 0
	s_mul_i32 s11, s73, 0x6000
	s_waitcnt lgkmcnt(4)
	v_mfma_f32_32x32x16_bf16 v[80:95], v[212:215], v[156:159], v[80:95]
	s_add_i32 s52, s11, 0
	v_exp_f32_e32 v229, v112
	v_exp_f32_e32 v230, v113
	v_exp_f32_e32 v231, v114
	v_exp_f32_e32 v232, v115
	s_add_i32 s11, s73, 1
	s_cmp_lg_u32 s73, 2
	s_cselect_b32 s11, s11, 0
	s_mul_i32 s11, s11, 0x6000
	s_add_i32 s11, s11, s69
	v_add_u32_e32 v233, s53, v201
	s_mov_b32 m0, s70
	ds_read_b128 v[112:115], v233 offset:32768
	ds_read_b128 v[212:215], v233 offset:45056
	buffer_load_dwordx4 v197, s[28:31], s51 offen lds
	s_waitcnt lgkmcnt(5)
	v_mfma_f32_32x32x16_bf16 v[64:79], v[208:211], v[152:155], v[64:79]
	s_waitcnt lgkmcnt(4)
	v_mfma_f32_32x32x16_bf16 v[80:95], v[216:219], v[152:155], v[80:95]
	v_exp_f32_e32 v234, v116
	v_exp_f32_e32 v235, v117
	v_exp_f32_e32 v236, v118
	v_exp_f32_e32 v237, v119
	s_mov_b32 m0, s71
	ds_read_b128 v[116:119], v205 offset:32896
	ds_read_b128 v[208:211], v205 offset:45184
	buffer_load_dwordx4 v198, s[28:31], s51 offen lds
	s_waitcnt lgkmcnt(5)
	v_mfma_f32_32x32x16_bf16 v[64:79], v[220:223], v[148:151], v[64:79]
	s_waitcnt lgkmcnt(4)
	v_mfma_f32_32x32x16_bf16 v[80:95], v[224:227], v[148:151], v[80:95]
	v_exp_f32_e32 v238, v120
	v_exp_f32_e32 v239, v121
	v_exp_f32_e32 v240, v122
	v_exp_f32_e32 v241, v123
	s_add_i32 m0, s11, 0x8000
	ds_read_b128 v[120:123], v207 offset:32896
	ds_read_b128 v[216:219], v207 offset:45184
	buffer_load_dwordx4 v194, s[28:31], s10 offen lds
	s_waitcnt lgkmcnt(5)
	v_mfma_f32_32x32x16_bf16 v[64:79], v[112:115], v[144:147], v[64:79]
	s_waitcnt lgkmcnt(4)
	v_mfma_f32_32x32x16_bf16 v[80:95], v[212:215], v[144:147], v[80:95]
	v_exp_f32_e32 v242, v124
	v_exp_f32_e32 v243, v125
	v_exp_f32_e32 v244, v126
	v_exp_f32_e32 v245, v127
	s_add_i32 m0, s11, 0xa000
	ds_read_b128 v[112:115], v228 offset:32896
	ds_read_b128 v[124:127], v228 offset:45184
	buffer_load_dwordx4 v195, s[28:31], s10 offen lds
	s_waitcnt lgkmcnt(5)
	v_mfma_f32_32x32x16_bf16 v[64:79], v[116:119], v[140:143], v[64:79]
	s_waitcnt lgkmcnt(4)
	v_mfma_f32_32x32x16_bf16 v[80:95], v[208:211], v[140:143], v[80:95]
	v_add_f32_e32 v116, 0, v96
	v_add_f32_e32 v116, v97, v116
	v_add_f32_e32 v116, v98, v116
	v_add_f32_e32 v116, v99, v116
	v_add_f32_e32 v116, v229, v116
	v_add_f32_e32 v116, v230, v116
	v_add_f32_e32 v116, v231, v116
	v_add_f32_e32 v212, v232, v116
	s_add_i32 m0, s11, 0xc000
	ds_read_b128 v[116:119], v233 offset:32896
	ds_read_b128 v[208:211], v233 offset:45184
	buffer_load_dwordx4 v196, s[28:31], s10 offen lds
	s_waitcnt lgkmcnt(5)
	v_mfma_f32_32x32x16_bf16 v[64:79], v[120:123], v[136:139], v[64:79]
	s_waitcnt lgkmcnt(4)
	v_mfma_f32_32x32x16_bf16 v[80:95], v[216:219], v[136:139], v[80:95]
	v_add_f32_e32 v120, v100, v212
	v_add_f32_e32 v120, v101, v120
	v_add_f32_e32 v120, v102, v120
	v_add_f32_e32 v120, v103, v120
	v_add_f32_e32 v120, v234, v120
	v_add_f32_e32 v120, v235, v120
	v_add_f32_e32 v120, v236, v120
	v_add_f32_e32 v216, v237, v120
	s_waitcnt lgkmcnt(3)
	v_mfma_f32_32x32x16_bf16 v[64:79], v[112:115], v[132:135], v[64:79]
	ds_read_b128 v[112:115], v205 offset:45312
	ds_read_b128 v[120:123], v205 offset:33024
	ds_read_b128 v[212:215], v192
	s_waitcnt lgkmcnt(5)
	v_mfma_f32_32x32x16_bf16 v[80:95], v[124:127], v[132:135], v[80:95]
	v_add_f32_e32 v124, v104, v216
	v_add_f32_e32 v124, v105, v124
	v_add_f32_e32 v124, v106, v124
	v_add_f32_e32 v124, v107, v124
	v_add_f32_e32 v124, v238, v124
	v_add_f32_e32 v124, v239, v124
	v_add_f32_e32 v124, v240, v124
	v_add_f32_e32 v205, v241, v124
	s_waitcnt lgkmcnt(4)
	v_mfma_f32_32x32x16_bf16 v[64:79], v[116:119], v[128:131], v[64:79]
	ds_read_b128 v[124:127], v207 offset:45312
	ds_read_b128 v[216:219], v207 offset:33024
	ds_read_b128 v[220:223], v192 offset:1024
	s_waitcnt lgkmcnt(6)
	v_mfma_f32_32x32x16_bf16 v[80:95], v[208:211], v[128:131], v[80:95]
	v_add_f32_e32 v116, v108, v205
	v_add_f32_e32 v116, v109, v116
	v_add_f32_e32 v116, v110, v116
	v_add_f32_e32 v116, v111, v116
	v_add_f32_e32 v116, v242, v116
	v_add_f32_e32 v116, v243, v116
	v_add_f32_e32 v116, v244, v116
	v_add_f32_e32 v116, v245, v116
	s_waitcnt lgkmcnt(3)
	v_mfma_f32_32x32x16_bf16 v[64:79], v[120:123], v[212:215], v[64:79]
	ds_read_b128 v[118:121], v228 offset:45312
	ds_read_b128 v[208:211], v228 offset:33024
	ds_read_b128 v[224:227], v192 offset:2048
	v_mfma_f32_32x32x16_bf16 v[80:95], v[112:115], v[212:215], v[80:95]
	v_mov_b32_e32 v117, v116
	v_cvt_pk_bf16_f32 v112, v96, v97
	v_cvt_pk_bf16_f32 v113, v98, v99
	v_cvt_pk_bf16_f32 v114, v100, v101
	v_cvt_pk_bf16_f32 v115, v102, v103
	v_permlane32_swap_b32_e32 v116, v117
	v_permlane32_swap_b32_e32 v112, v114
	v_permlane32_swap_b32_e32 v113, v115
	s_waitcnt lgkmcnt(3)
; #define SBAR() __builtin_amdgcn_sched_barrier(0)
; template <int I> __device__ __forceinline__ void ps_chunk(f32x16& p0, f32x16& p1, float& M, float& alpha, SMState& st) {
;   if constexpr (I == 0) { float m = p0[0];
; #pragma unroll
;     for (int r = 1; r < 16; ++r) m = fmaxf(m, p0[r]);
;     st.pmax = m;
;   } else if constexpr (I == 1) { float m = st.pmax;
; #pragma unroll
;     for (int r = 0; r < 16; ++r) m = fmaxf(m, p1[r]);
;     auto rr = __builtin_amdgcn_permlane32_swap(__float_as_uint(m), __float_as_uint(m), false, false);
;     st.pmax = fmaxf(__uint_as_float(rr[0]), __uint_as_float(rr[1]));
;   } else if constexpr (I == 2) {
;     alpha = 1.f;
;     if (__builtin_expect(!__all(st.pmax <= THR2), 0)) { const float d = fmaxf(st.pmax, 0.f); M += d; alpha = __builtin_amdgcn_exp2f(-d);
; #pragma unroll
;       for (int r = 0; r < 16; ++r) { p0[r] -= d; p1[r] -= d; } }
; template <int G> __device__ __forceinline__ void v_load(s16x4& la, s16x4& ha, s16x4& lb, s16x4& hb, const __attribute__((address_space(3))) char* vb) {
;   constexpr int ks = G >> 1, d0 = (G & 1) * 2;
;   la = __builtin_amdgcn_ds_read_tr16_b64_v4i16((lds_s16x4b*)(vb + v_rd_off(d0, ks, 0))); ha = __builtin_amdgcn_ds_read_tr16_b64_v4i16((lds_s16x4b*)(vb + v_rd_off(d0, ks, 1)));
;   lb = __builtin_amdgcn_ds_read_tr16_b64_v4i16((lds_s16x4b*)(vb + v_rd_off(d0 + 1, ks, 0))); hb = __builtin_amdgcn_ds_read_tr16_b64_v4i16((lds_s16x4b*)(vb + v_rd_off(d0 + 1, ks, 1)));
; }
; template <int G> __device__ __forceinline__ void h2_stage(f32x16* o, f32x16& pc0, f32x16& pc1, float& m_reg, float& alC, SMState& st, bf16x8 pa0, bf16x8 pa1, bf16x8 pa2, bf16x8 pa3, ...
;   constexpr int ks = G >> 1, d0 = (G & 1) * 2;
;   s16x4 nla, nha, nlb, nhb;
;   if constexpr (G < 7) v_load<G + 1>(nla, nha, nlb, nhb, vb);
;   const bf16x8 pa = ks == 0 ? pa0 : ks == 1 ? pa1 : ks == 2 ? pa2 : pa3;
;     ...
;   o[d0] = __builtin_amdgcn_mfma_f32_32x32x16_bf16(pa, PK(la, ha), o[d0], 0, 0, 0);
;   o[d0 + 1] = __builtin_amdgcn_mfma_f32_32x32x16_bf16(pa, PK(lb, hb), o[d0 + 1], 0, 0, 0);
;     ...
;   SBAR(); ps_chunk<G>(pc0, pc1, m_reg, alC, st); SBAR();
;   if constexpr (G < 7) h2_stage<G + 1>(o, pc0, pc1, m_reg, alC, st, pa0, pa1, pa2, pa3, nla, nha, nlb, nhb, vb);
; }
	v_mfma_f32_32x32x16_bf16 v[64:79], v[216:219], v[220:223], v[64:79]
	ds_read_b128 v[96:99], v192 offset:3072
	ds_read_b128 v[212:215], v233 offset:33024
	ds_read_b128 v[216:219], v233 offset:45312
	v_mfma_f32_32x32x16_bf16 v[80:95], v[124:127], v[220:223], v[80:95]
	v_cvt_pk_bf16_f32 v104, v104, v105
	v_cvt_pk_bf16_f32 v105, v106, v107
	v_cvt_pk_bf16_f32 v106, v108, v109
	v_cvt_pk_bf16_f32 v107, v110, v111
	s_nop 0
	v_permlane32_swap_b32_e32 v104, v106
	v_permlane32_swap_b32_e32 v105, v107
	s_waitcnt lgkmcnt(3)
	v_mfma_f32_32x32x16_bf16 v[64:79], v[208:211], v[224:227], v[64:79]
	v_mfma_f32_32x32x16_bf16 v[80:95], v[118:121], v[224:227], v[80:95]
	v_cvt_pk_bf16_f32 v100, v229, v230
	v_cvt_pk_bf16_f32 v101, v231, v232
	v_cvt_pk_bf16_f32 v102, v234, v235
	v_cvt_pk_bf16_f32 v103, v236, v237
	s_nop 0
	v_permlane32_swap_b32_e32 v100, v102
	v_permlane32_swap_b32_e32 v101, v103
	s_waitcnt lgkmcnt(1)
	v_mfma_f32_32x32x16_bf16 v[64:79], v[212:215], v[96:99], v[64:79]
	s_waitcnt lgkmcnt(0)
	v_mfma_f32_32x32x16_bf16 v[80:95], v[216:219], v[96:99], v[80:95]
	v_cvt_pk_bf16_f32 v96, v238, v239
	v_cvt_pk_bf16_f32 v97, v240, v241
	v_cvt_pk_bf16_f32 v98, v242, v243
	v_cvt_pk_bf16_f32 v99, v244, v245
	s_nop 0
	v_permlane32_swap_b32_e32 v96, v98
	v_permlane32_swap_b32_e32 v97, v99
	ds_read_b64_tr_b16 v[110:111], v188 offset:18432
	ds_read_b64_tr_b16 v[108:109], v188 offset:16384
	ds_read_b64_tr_b16 v[118:119], v188 offset:16896
	ds_read_b64_tr_b16 v[122:123], v188 offset:17408
	ds_read_b64_tr_b16 v[208:209], v188 offset:17920
	ds_read_b64_tr_b16 v[120:121], v188 offset:18944
	ds_read_b64_tr_b16 v[124:125], v188 offset:19456
	ds_read_b64_tr_b16 v[210:211], v188 offset:19968
	s_waitcnt lgkmcnt(6)
	v_mfma_f32_32x32x16_bf16 v[0:15], v[112:115], v[108:111], v[0:15]
	s_waitcnt lgkmcnt(2)
	v_mfma_f32_32x32x16_bf16 v[48:63], v[112:115], v[118:121], v[48:63]
	v_max_f32_e32 v108, v65, v65
	v_max_f32_e32 v109, v64, v64
	v_max_f32_e32 v108, v109, v108
	v_max3_f32 v108, v108, v66, v67
	v_max3_f32 v108, v108, v68, v69
	v_max3_f32 v108, v108, v70, v71
	v_max3_f32 v108, v108, v72, v73
	v_max3_f32 v108, v108, v74, v75
	v_max3_f32 v108, v108, v76, v77
	v_max3_f32 v118, v108, v78, v79
	s_waitcnt lgkmcnt(1)
	v_mfma_f32_32x32x16_bf16 v[32:47], v[112:115], v[122:125], v[32:47]
	ds_read_b64_tr_b16 v[108:109], v188 offset:20480
	ds_read_b64_tr_b16 v[110:111], v188 offset:22528
	ds_read_b64_tr_b16 v[122:123], v188 offset:23040
	ds_read_b64_tr_b16 v[120:121], v188 offset:20992
	s_waitcnt lgkmcnt(4)
	v_mfma_f32_32x32x16_bf16 v[16:31], v[112:115], v[208:211], v[16:31]
	v_max3_f32 v112, v118, v80, v81
	v_max3_f32 v112, v112, v82, v83
	v_max3_f32 v112, v112, v84, v85
	v_max3_f32 v112, v112, v86, v87
	v_max3_f32 v112, v112, v88, v89
	v_max3_f32 v112, v112, v90, v91
	v_max3_f32 v112, v112, v92, v93
	v_max3_f32 v112, v112, v94, v95
	v_mov_b32_e32 v113, v112
	s_nop 1
	v_permlane32_swap_b32_e32 v112, v113
	v_max_f32_e32 v113, v113, v113
	v_max_f32_e32 v112, v112, v112
	v_max_f32_e32 v118, v112, v113
	s_waitcnt lgkmcnt(2)
	v_mfma_f32_32x32x16_bf16 v[0:15], v[104:107], v[108:111], v[0:15]
	ds_read_b64_tr_b16 v[112:113], v188 offset:21504
	ds_read_b64_tr_b16 v[114:115], v188 offset:23552
	ds_read_b64_tr_b16 v[110:111], v188 offset:24064
	ds_read_b64_tr_b16 v[108:109], v188 offset:22016
	s_waitcnt lgkmcnt(4)
	v_mfma_f32_32x32x16_bf16 v[48:63], v[104:107], v[120:123], v[48:63]
	v_cmp_ge_f32_e32 vcc, s67, v118
	s_cmp_eq_u64 vcc, exec
	v_mov_b32_e32 v205, 1.0
	s_cbranch_scc0 .LBB0_669
; #define DMAK(t, s) do { dc.gk = (unsigned)((size_t)(t) * TILEB); dc.kd = K_lds + (s) * SHM_K; dma_piece<0>(dc); dma_piece<1>(dc); dma_piece<2>(dc); } while (0)
; #define DMAV(t, s) do { dc.gv = (unsigned)((size_t)(t) * TILEB); dc.vd = V_lds + (s) * SHM_V; dma_piece<3>(dc); dma_piece<4>(dc); } while (0)
; #define BAR() do { asm volatile("s_waitcnt lgkmcnt(0)" ::: "memory"); __builtin_amdgcn_s_barrier(); asm volatile("" ::: "memory"); } while (0)
; __device__ __forceinline__ void attn_body(const bf16_t* __restrict__ Qb, const bf16_t* __restrict__ KVb, int hcol, bf16_t* __restrict__ Ob, float* __restrict__ rsqa, int seq, char* lds) {
;     ...
;   f32x16 pA0, pA1, pB0, pB1; float alA, alB; bf16x8 pa0, pa1, pa2, pa3; SMState st; const int NT = seq / KVBLK;
;   DMAK(0, 0); DMAV(0, 0); DMAK(1, 1);
;   asm volatile("s_waitcnt vmcnt(3)" ::: "memory"); BAR();
;   qkt(pA0, pA1, K_lds, qr, qlds, kb); partialSM0(pA0, pA1, m_reg); alA = 1.f;
;   asm volatile("s_waitcnt vmcnt(0)" ::: "memory"); BAR();
;   int sc = 1;
;   for (int j = 1; j + 1 < NT; j += 2) {
;     STEP(pB0, pB1, alB, pA0, pA1, alA, j, sc, 0);
;     sc = NEXT3(sc);
;     STEP(pA0, pA1, alA, pB0, pB1, alB, j + 1, sc, 1);
;     sc = NEXT3(sc);
;   }
.LBB0_662:
	v_exp_f32_e32 v64, v64
	v_exp_f32_e32 v65, v65
	s_waitcnt lgkmcnt(2)
	v_mfma_f32_32x32x16_bf16 v[32:47], v[104:107], v[112:115], v[32:47]
	ds_read_b64_tr_b16 v[112:113], v188 offset:24576
	ds_read_b64_tr_b16 v[114:115], v188 offset:26624
	ds_read_b64_tr_b16 v[120:121], v188 offset:27136
	ds_read_b64_tr_b16 v[118:119], v188 offset:25088
	s_waitcnt lgkmcnt(4)
	v_mfma_f32_32x32x16_bf16 v[16:31], v[104:107], v[108:111], v[16:31]
	v_exp_f32_e32 v66, v66
	v_exp_f32_e32 v67, v67
	v_exp_f32_e32 v68, v68
	s_waitcnt lgkmcnt(2)
	v_mfma_f32_32x32x16_bf16 v[0:15], v[100:103], v[112:115], v[0:15]
	ds_read_b64_tr_b16 v[104:105], v188 offset:25600
	ds_read_b64_tr_b16 v[106:107], v188 offset:27648
	ds_read_b64_tr_b16 v[110:111], v188 offset:28160
	ds_read_b64_tr_b16 v[108:109], v188 offset:26112
	s_waitcnt lgkmcnt(4)
	v_mfma_f32_32x32x16_bf16 v[48:63], v[100:103], v[118:121], v[48:63]
	v_exp_f32_e32 v69, v69
	v_exp_f32_e32 v70, v70
	v_exp_f32_e32 v71, v71
	s_waitcnt lgkmcnt(2)
	v_mfma_f32_32x32x16_bf16 v[32:47], v[100:103], v[104:107], v[32:47]
	ds_read_b64_tr_b16 v[104:105], v188 offset:28672
	ds_read_b64_tr_b16 v[106:107], v188 offset:30720
	ds_read_b64_tr_b16 v[114:115], v188 offset:31232
	ds_read_b64_tr_b16 v[112:113], v188 offset:29184
	s_waitcnt lgkmcnt(4)
	v_mfma_f32_32x32x16_bf16 v[16:31], v[100:103], v[108:111], v[16:31]
	v_exp_f32_e32 v72, v72
	v_exp_f32_e32 v73, v73
	v_exp_f32_e32 v74, v74
	s_waitcnt lgkmcnt(2)
	v_mfma_f32_32x32x16_bf16 v[0:15], v[96:99], v[104:107], v[0:15]
	ds_read_b64_tr_b16 v[100:101], v188 offset:29696
	ds_read_b64_tr_b16 v[102:103], v188 offset:31744
	ds_read_b64_tr_b16 v[106:107], v188 offset:32256
	ds_read_b64_tr_b16 v[104:105], v188 offset:30208
	s_waitcnt lgkmcnt(4)
	v_exp_f32_e32 v75, v75
	v_exp_f32_e32 v76, v76
	v_exp_f32_e32 v77, v77
	s_waitcnt lgkmcnt(0)
	v_exp_f32_e32 v78, v78
	v_exp_f32_e32 v79, v79
	s_waitcnt vmcnt(3)
	v_cmp_gt_f32_e32 vcc, 1.0, v205
	s_cbranch_vccz .Lattn_n2
	v_mfma_f32_32x32x16_bf16 v[48:63], v[96:99], v[112:115], v[48:63]
	v_mfma_f32_32x32x16_bf16 v[32:47], v[96:99], v[100:103], v[32:47]
	v_mfma_f32_32x32x16_bf16 v[16:31], v[96:99], v[104:107], v[16:31]
	s_nop 15
	s_nop 15
	s_and_saveexec_b64 s[10:11], s[4:5]
	ds_write_b32 v189, v205 offset:128
	s_or_b64 exec, exec, s[10:11]
	s_waitcnt lgkmcnt(0)
	v_add_u32_e32 v108, s1, v166
	ds_read_b128 v[96:99], v108 offset:224
	ds_read_b128 v[100:103], v108 offset:192
	ds_read_b128 v[104:107], v108 offset:160
	ds_read_b128 v[108:111], v108 offset:128
	s_waitcnt lgkmcnt(3)
	v_pk_mul_f32 v[12:13], v[12:13], v[96:97]
	s_waitcnt lgkmcnt(2)
	v_pk_mul_f32 v[8:9], v[8:9], v[100:101]
	s_waitcnt lgkmcnt(1)
	v_pk_mul_f32 v[4:5], v[4:5], v[104:105]
	v_pk_mul_f32 v[14:15], v[14:15], v[98:99]
	v_pk_mul_f32 v[10:11], v[10:11], v[102:103]
	v_pk_mul_f32 v[6:7], v[6:7], v[106:107]
	s_waitcnt lgkmcnt(0)
	v_pk_mul_f32 v[2:3], v[2:3], v[110:111]
	v_pk_mul_f32 v[0:1], v[0:1], v[108:109]
	v_pk_mul_f32 v[60:61], v[60:61], v[96:97]
	v_pk_mul_f32 v[56:57], v[56:57], v[100:101]
	v_pk_mul_f32 v[52:53], v[52:53], v[104:105]
	v_pk_mul_f32 v[62:63], v[62:63], v[98:99]
	v_pk_mul_f32 v[58:59], v[58:59], v[102:103]
	v_pk_mul_f32 v[54:55], v[54:55], v[106:107]
	v_pk_mul_f32 v[50:51], v[50:51], v[110:111]
	v_pk_mul_f32 v[48:49], v[48:49], v[108:109]
	v_pk_mul_f32 v[44:45], v[44:45], v[96:97]
	v_pk_mul_f32 v[40:41], v[40:41], v[100:101]
	v_pk_mul_f32 v[36:37], v[36:37], v[104:105]
	v_pk_mul_f32 v[46:47], v[46:47], v[98:99]
	v_pk_mul_f32 v[42:43], v[42:43], v[102:103]
	v_pk_mul_f32 v[38:39], v[38:39], v[106:107]
	v_pk_mul_f32 v[34:35], v[34:35], v[110:111]
	v_pk_mul_f32 v[32:33], v[32:33], v[108:109]
	v_pk_mul_f32 v[28:29], v[28:29], v[96:97]
	v_pk_mul_f32 v[24:25], v[24:25], v[100:101]
	v_pk_mul_f32 v[20:21], v[20:21], v[104:105]
	v_pk_mul_f32 v[30:31], v[30:31], v[98:99]
	v_pk_mul_f32 v[26:27], v[26:27], v[102:103]
	v_pk_mul_f32 v[22:23], v[22:23], v[106:107]
	v_pk_mul_f32 v[18:19], v[18:19], v[110:111]
	v_pk_mul_f32 v[16:17], v[16:17], v[108:109]
	v_add_f32_e32 v243, v203, v204
	v_fmac_f32_e32 v243, v190, v202
	v_add_f32_e32 v190, v116, v117
	v_fmac_f32_e32 v190, v243, v206
	v_mov_b32_e32 v202, v205
	s_add_i32 s51, s51, 0x84000
	s_add_i32 s72, s72, 2
	s_mul_i32 s98, s73, 0x6000
	v_add_u32_e32 v203, s98, v193
	s_waitcnt lgkmcnt(0)
	s_barrier
	s_cmp_ge_u32 s72, s37
	s_cbranch_scc1 .LBB0_670
	ds_read_b128 v[204:207], v203 offset:32768
	ds_read_b128 v[208:211], v203 offset:45056
	s_add_i32 s10, s73, 1
	s_cmp_lg_u32 s73, 2
	s_cselect_b32 s52, s10, 0
	s_mov_b32 s10, s98
	s_branch .Lattn_m2
